# baseline (speedup 1.0000x reference)
.Lhp_ft:
	v_and_b32_e32 v94, 31, v93
	v_bfe_u32 v95, v93, 5, 1
	v_lshrrev_b32_e32 v96, 6, v93
	s_nop 0
	v_readfirstlane_b32 s0, v96
	s_lshl_b32 s1, s2, 2
	s_add_u32 s0, s0, s1
	s_and_b32 s17, s0, 127
	s_lshl_b32 s17, s17, 5
	s_lshr_b32 s20, s0, 7
	v_add_u32_e32 v96, s17, v94
	v_lshlrev_b32_e32 v96, 2, v96
	v_lshl_add_u32 v97, v95, 19, v96
	v_lshlrev_b32_e32 v98, 8, v94
	v_lshl_add_u32 v98, v95, 7, v98
	v_lshlrev_b32_e32 v96, 2, v94
	v_lshl_add_u32 v99, v95, 16, v96
	v_lshl_add_u32 v100, v95, 12, v96
	v_readlane_b32 s15, v233, 25
	v_readlane_b32 s4, v236, 39
	v_readlane_b32 s5, v236, 40
	s_lshl_b32 s0, s15, 20
	s_add_u32 s4, s4, s0
	s_addc_u32 s5, s5, 0
	v_readlane_b32 s6, v235, 39
	v_readlane_b32 s7, v235, 40
	s_mul_i32 s0, s15, 0x110000
	s_add_u32 s6, s6, s0
	s_addc_u32 s7, s7, 0
	v_readlane_b32 s8, v235, 41
	v_readlane_b32 s9, v235, 42
	s_add_u32 s0, s4, 0x0
	s_addc_u32 s1, s5, 0
	global_load_dword v0, v97, s[0:1]
	s_add_u32 s0, s4, 0x4000
	s_addc_u32 s1, s5, 0
	global_load_dword v1, v97, s[0:1]
	s_add_u32 s0, s4, 0x8000
	s_addc_u32 s1, s5, 0
	global_load_dword v2, v97, s[0:1]
	s_add_u32 s0, s4, 0xc000
	s_addc_u32 s1, s5, 0
	global_load_dword v3, v97, s[0:1]
	s_add_u32 s0, s4, 0x10000
	s_addc_u32 s1, s5, 0
	global_load_dword v4, v97, s[0:1]
	s_add_u32 s0, s4, 0x14000
	s_addc_u32 s1, s5, 0
	global_load_dword v5, v97, s[0:1]
	s_add_u32 s0, s4, 0x18000
	s_addc_u32 s1, s5, 0
	global_load_dword v6, v97, s[0:1]
	s_add_u32 s0, s4, 0x1c000
	s_addc_u32 s1, s5, 0
	global_load_dword v7, v97, s[0:1]
	s_add_u32 s0, s4, 0x20000
	s_addc_u32 s1, s5, 0
	global_load_dword v8, v97, s[0:1]
	s_add_u32 s0, s4, 0x24000
	s_addc_u32 s1, s5, 0
	global_load_dword v9, v97, s[0:1]
	s_add_u32 s0, s4, 0x28000
	s_addc_u32 s1, s5, 0
	global_load_dword v10, v97, s[0:1]
	s_add_u32 s0, s4, 0x2c000
	s_addc_u32 s1, s5, 0
	global_load_dword v11, v97, s[0:1]
	s_add_u32 s0, s4, 0x30000
	s_addc_u32 s1, s5, 0
	global_load_dword v12, v97, s[0:1]
	s_add_u32 s0, s4, 0x34000
	s_addc_u32 s1, s5, 0
	global_load_dword v13, v97, s[0:1]
	s_add_u32 s0, s4, 0x38000
	s_addc_u32 s1, s5, 0
	global_load_dword v14, v97, s[0:1]
	s_add_u32 s0, s4, 0x3c000
	s_addc_u32 s1, s5, 0
	global_load_dword v15, v97, s[0:1]
	s_add_u32 s0, s4, 0x40000
	s_addc_u32 s1, s5, 0
	global_load_dword v16, v97, s[0:1]
	s_add_u32 s0, s4, 0x44000
	s_addc_u32 s1, s5, 0
	global_load_dword v17, v97, s[0:1]
	s_add_u32 s0, s4, 0x48000
	s_addc_u32 s1, s5, 0
	global_load_dword v18, v97, s[0:1]
	s_add_u32 s0, s4, 0x4c000
	s_addc_u32 s1, s5, 0
	global_load_dword v19, v97, s[0:1]
	s_add_u32 s0, s4, 0x50000
	s_addc_u32 s1, s5, 0
	global_load_dword v20, v97, s[0:1]
	s_add_u32 s0, s4, 0x54000
	s_addc_u32 s1, s5, 0
	global_load_dword v21, v97, s[0:1]
	s_add_u32 s0, s4, 0x58000
	s_addc_u32 s1, s5, 0
	global_load_dword v22, v97, s[0:1]
	s_add_u32 s0, s4, 0x5c000
	s_addc_u32 s1, s5, 0
	global_load_dword v23, v97, s[0:1]
	s_add_u32 s0, s4, 0x60000
	s_addc_u32 s1, s5, 0
	global_load_dword v24, v97, s[0:1]
	s_add_u32 s0, s4, 0x64000
	s_addc_u32 s1, s5, 0
	global_load_dword v25, v97, s[0:1]
	s_add_u32 s0, s4, 0x68000
	s_addc_u32 s1, s5, 0
	global_load_dword v26, v97, s[0:1]
	s_add_u32 s0, s4, 0x6c000
	s_addc_u32 s1, s5, 0
	global_load_dword v27, v97, s[0:1]
	s_add_u32 s0, s4, 0x70000
	s_addc_u32 s1, s5, 0
	global_load_dword v28, v97, s[0:1]
	s_add_u32 s0, s4, 0x74000
	s_addc_u32 s1, s5, 0
	global_load_dword v29, v97, s[0:1]
	s_add_u32 s0, s4, 0x78000
	s_addc_u32 s1, s5, 0
	global_load_dword v30, v97, s[0:1]
	s_add_u32 s0, s4, 0x7c000
	s_addc_u32 s1, s5, 0
	global_load_dword v31, v97, s[0:1]
	s_mov_b32 s14, 0
	s_movk_i32 s15, 8
	s_cmpk_lt_u32 s20, 8
	s_addc_u32 s15, s15, 0
	s_lshl_b32 s0, s20, 3
	s_add_u32 s0, s0, s14
	s_lshl_b32 s12, s0, 5
	s_mov_b32 s13, s12
	s_lshl_b32 s0, s20, 5
	s_add_u32 s1, s0, 0x1000
	s_cmp_eq_u32 s14, 8
	s_cselect_b32 s18, 1, 0
	s_cselect_b32 s12, s0, s12
	s_cselect_b32 s13, s1, s13
	s_lshl_b32 s0, s13, 8
	s_add_u32 s10, s6, s0
	s_addc_u32 s11, s7, 0
	global_load_dwordx4 v[32:35], v98, s[10:11] offset:0
	global_load_dwordx4 v[36:39], v98, s[10:11] offset:16
	global_load_dwordx4 v[40:43], v98, s[10:11] offset:32
	global_load_dwordx4 v[44:47], v98, s[10:11] offset:48
	global_load_dwordx4 v[48:51], v98, s[10:11] offset:64
	global_load_dwordx4 v[52:55], v98, s[10:11] offset:80
	global_load_dwordx4 v[56:59], v98, s[10:11] offset:96
	global_load_dwordx4 v[60:63], v98, s[10:11] offset:112
	s_waitcnt vmcnt(0)
.Lhp_ft_tile:
	s_add_u32 s19, s14, 1
	s_cmp_lt_u32 s19, s15
	s_cbranch_scc0 .Lhp_ft_np0
	s_lshl_b32 s0, s20, 3
	s_add_u32 s0, s0, s19
	s_lshl_b32 s12, s0, 5
	s_mov_b32 s13, s12
	s_lshl_b32 s0, s20, 5
	s_add_u32 s1, s0, 0x1000
	s_cmp_eq_u32 s19, 8
	s_cselect_b32 s18, 1, 0
	s_cselect_b32 s12, s0, s12
	s_cselect_b32 s13, s1, s13
	s_lshl_b32 s0, s13, 8
	s_add_u32 s10, s6, s0
	s_addc_u32 s11, s7, 0
	global_load_dwordx4 v[102:105], v98, s[10:11] offset:0
	global_load_dwordx4 v[106:109], v98, s[10:11] offset:16
	global_load_dwordx4 v[110:113], v98, s[10:11] offset:32
	global_load_dwordx4 v[114:117], v98, s[10:11] offset:48
	global_load_dwordx4 v[118:121], v98, s[10:11] offset:64
	global_load_dwordx4 v[122:125], v98, s[10:11] offset:80
	global_load_dwordx4 v[126:129], v98, s[10:11] offset:96
	global_load_dwordx4 v[130:133], v98, s[10:11] offset:112
.Lhp_ft_np0:
	v_mfma_f32_32x32x2_f32 v[64:79], v0, v32, 0
	v_mfma_f32_32x32x2_f32 v[64:79], v1, v33, v[64:79]
	v_mfma_f32_32x32x2_f32 v[64:79], v2, v34, v[64:79]
	v_mfma_f32_32x32x2_f32 v[64:79], v3, v35, v[64:79]
	v_mfma_f32_32x32x2_f32 v[64:79], v4, v36, v[64:79]
	v_mfma_f32_32x32x2_f32 v[64:79], v5, v37, v[64:79]
	v_mfma_f32_32x32x2_f32 v[64:79], v6, v38, v[64:79]
	v_mfma_f32_32x32x2_f32 v[64:79], v7, v39, v[64:79]
	v_mfma_f32_32x32x2_f32 v[64:79], v8, v40, v[64:79]
	v_mfma_f32_32x32x2_f32 v[64:79], v9, v41, v[64:79]
	v_mfma_f32_32x32x2_f32 v[64:79], v10, v42, v[64:79]
	v_mfma_f32_32x32x2_f32 v[64:79], v11, v43, v[64:79]
	v_mfma_f32_32x32x2_f32 v[64:79], v12, v44, v[64:79]
	v_mfma_f32_32x32x2_f32 v[64:79], v13, v45, v[64:79]
	v_mfma_f32_32x32x2_f32 v[64:79], v14, v46, v[64:79]
	v_mfma_f32_32x32x2_f32 v[64:79], v15, v47, v[64:79]
	v_mfma_f32_32x32x2_f32 v[64:79], v16, v48, v[64:79]
	v_mfma_f32_32x32x2_f32 v[64:79], v17, v49, v[64:79]
	v_mfma_f32_32x32x2_f32 v[64:79], v18, v50, v[64:79]
	v_mfma_f32_32x32x2_f32 v[64:79], v19, v51, v[64:79]
	v_mfma_f32_32x32x2_f32 v[64:79], v20, v52, v[64:79]
	v_mfma_f32_32x32x2_f32 v[64:79], v21, v53, v[64:79]
	v_mfma_f32_32x32x2_f32 v[64:79], v22, v54, v[64:79]
	v_mfma_f32_32x32x2_f32 v[64:79], v23, v55, v[64:79]
	v_mfma_f32_32x32x2_f32 v[64:79], v24, v56, v[64:79]
	v_mfma_f32_32x32x2_f32 v[64:79], v25, v57, v[64:79]
	v_mfma_f32_32x32x2_f32 v[64:79], v26, v58, v[64:79]
	v_mfma_f32_32x32x2_f32 v[64:79], v27, v59, v[64:79]
	v_mfma_f32_32x32x2_f32 v[64:79], v28, v60, v[64:79]
	v_mfma_f32_32x32x2_f32 v[64:79], v29, v61, v[64:79]
	v_mfma_f32_32x32x2_f32 v[64:79], v30, v62, v[64:79]
	v_mfma_f32_32x32x2_f32 v[64:79], v31, v63, v[64:79]
	s_lshl_b32 s0, s20, 3
	s_add_u32 s0, s0, s14
	s_lshl_b32 s12, s0, 5
	s_mov_b32 s13, s12
	s_lshl_b32 s0, s20, 5
	s_add_u32 s1, s0, 0x1000
	s_cmp_eq_u32 s14, 8
	s_cselect_b32 s18, 1, 0
	s_cselect_b32 s12, s0, s12
	s_cselect_b32 s13, s1, s13
	s_nop 15
	s_nop 3
	s_cmp_lg_u32 s18, 0
	s_cbranch_scc1 .Lhp_ft_ctx0
	s_lshl_b32 s0, s17, 12
	s_add_u32 s0, s0, s12
	s_lshl_b32 s0, s0, 2
	s_add_u32 s10, s8, s0
	s_addc_u32 s11, s9, 0
	s_add_u32 s0, s10, 0x0
	s_addc_u32 s1, s11, 0
	global_store_dword v99, v64, s[0:1]
	s_add_u32 s0, s10, 0x4000
	s_addc_u32 s1, s11, 0
	global_store_dword v99, v65, s[0:1]
	s_add_u32 s0, s10, 0x8000
	s_addc_u32 s1, s11, 0
	global_store_dword v99, v66, s[0:1]
	s_add_u32 s0, s10, 0xc000
	s_addc_u32 s1, s11, 0
	global_store_dword v99, v67, s[0:1]
	s_add_u32 s0, s10, 0x20000
	s_addc_u32 s1, s11, 0
	global_store_dword v99, v68, s[0:1]
	s_add_u32 s0, s10, 0x24000
	s_addc_u32 s1, s11, 0
	global_store_dword v99, v69, s[0:1]
	s_add_u32 s0, s10, 0x28000
	s_addc_u32 s1, s11, 0
	global_store_dword v99, v70, s[0:1]
	s_add_u32 s0, s10, 0x2c000
	s_addc_u32 s1, s11, 0
	global_store_dword v99, v71, s[0:1]
	s_add_u32 s0, s10, 0x40000
	s_addc_u32 s1, s11, 0
	global_store_dword v99, v72, s[0:1]
	s_add_u32 s0, s10, 0x44000
	s_addc_u32 s1, s11, 0
	global_store_dword v99, v73, s[0:1]
	s_add_u32 s0, s10, 0x48000
	s_addc_u32 s1, s11, 0
	global_store_dword v99, v74, s[0:1]
	s_add_u32 s0, s10, 0x4c000
	s_addc_u32 s1, s11, 0
	global_store_dword v99, v75, s[0:1]
	s_add_u32 s0, s10, 0x60000
	s_addc_u32 s1, s11, 0
	global_store_dword v99, v76, s[0:1]
	s_add_u32 s0, s10, 0x64000
	s_addc_u32 s1, s11, 0
	global_store_dword v99, v77, s[0:1]
	s_add_u32 s0, s10, 0x68000
	s_addc_u32 s1, s11, 0
	global_store_dword v99, v78, s[0:1]
	s_add_u32 s0, s10, 0x6c000
	s_addc_u32 s1, s11, 0
	global_store_dword v99, v79, s[0:1]
	s_branch .Lhp_ft_next0

.Lhp_ft_next0:
	s_waitcnt vmcnt(16)
	s_add_u32 s14, s14, 1
	s_cmp_lt_u32 s14, s15
	s_cbranch_scc0 .Lhp_ft_done
	s_add_u32 s19, s14, 1
	s_cmp_lt_u32 s19, s15
	s_cbranch_scc0 .Lhp_ft_np1
	s_lshl_b32 s0, s20, 3
	s_add_u32 s0, s0, s19
	s_lshl_b32 s12, s0, 5
	s_mov_b32 s13, s12
	s_lshl_b32 s0, s20, 5
	s_add_u32 s1, s0, 0x1000
	s_cmp_eq_u32 s19, 8
	s_cselect_b32 s18, 1, 0
	s_cselect_b32 s12, s0, s12
	s_cselect_b32 s13, s1, s13
	s_lshl_b32 s0, s13, 8
	s_add_u32 s10, s6, s0
	s_addc_u32 s11, s7, 0
	global_load_dwordx4 v[32:35], v98, s[10:11] offset:0
	global_load_dwordx4 v[36:39], v98, s[10:11] offset:16
	global_load_dwordx4 v[40:43], v98, s[10:11] offset:32
	global_load_dwordx4 v[44:47], v98, s[10:11] offset:48
	global_load_dwordx4 v[48:51], v98, s[10:11] offset:64
	global_load_dwordx4 v[52:55], v98, s[10:11] offset:80
	global_load_dwordx4 v[56:59], v98, s[10:11] offset:96
	global_load_dwordx4 v[60:63], v98, s[10:11] offset:112
.Lhp_ft_np1:
	v_mfma_f32_32x32x2_f32 v[64:79], v0, v102, 0
	v_mfma_f32_32x32x2_f32 v[64:79], v1, v103, v[64:79]
	v_mfma_f32_32x32x2_f32 v[64:79], v2, v104, v[64:79]
	v_mfma_f32_32x32x2_f32 v[64:79], v3, v105, v[64:79]
	v_mfma_f32_32x32x2_f32 v[64:79], v4, v106, v[64:79]
	v_mfma_f32_32x32x2_f32 v[64:79], v5, v107, v[64:79]
	v_mfma_f32_32x32x2_f32 v[64:79], v6, v108, v[64:79]
	v_mfma_f32_32x32x2_f32 v[64:79], v7, v109, v[64:79]
	v_mfma_f32_32x32x2_f32 v[64:79], v8, v110, v[64:79]
	v_mfma_f32_32x32x2_f32 v[64:79], v9, v111, v[64:79]
	v_mfma_f32_32x32x2_f32 v[64:79], v10, v112, v[64:79]
	v_mfma_f32_32x32x2_f32 v[64:79], v11, v113, v[64:79]
	v_mfma_f32_32x32x2_f32 v[64:79], v12, v114, v[64:79]
	v_mfma_f32_32x32x2_f32 v[64:79], v13, v115, v[64:79]
	v_mfma_f32_32x32x2_f32 v[64:79], v14, v116, v[64:79]
	v_mfma_f32_32x32x2_f32 v[64:79], v15, v117, v[64:79]
	v_mfma_f32_32x32x2_f32 v[64:79], v16, v118, v[64:79]
	v_mfma_f32_32x32x2_f32 v[64:79], v17, v119, v[64:79]
	v_mfma_f32_32x32x2_f32 v[64:79], v18, v120, v[64:79]
	v_mfma_f32_32x32x2_f32 v[64:79], v19, v121, v[64:79]
	v_mfma_f32_32x32x2_f32 v[64:79], v20, v122, v[64:79]
	v_mfma_f32_32x32x2_f32 v[64:79], v21, v123, v[64:79]
	v_mfma_f32_32x32x2_f32 v[64:79], v22, v124, v[64:79]
	v_mfma_f32_32x32x2_f32 v[64:79], v23, v125, v[64:79]
	v_mfma_f32_32x32x2_f32 v[64:79], v24, v126, v[64:79]
	v_mfma_f32_32x32x2_f32 v[64:79], v25, v127, v[64:79]
	v_mfma_f32_32x32x2_f32 v[64:79], v26, v128, v[64:79]
	v_mfma_f32_32x32x2_f32 v[64:79], v27, v129, v[64:79]
	v_mfma_f32_32x32x2_f32 v[64:79], v28, v130, v[64:79]
	v_mfma_f32_32x32x2_f32 v[64:79], v29, v131, v[64:79]
	v_mfma_f32_32x32x2_f32 v[64:79], v30, v132, v[64:79]
	v_mfma_f32_32x32x2_f32 v[64:79], v31, v133, v[64:79]
	s_lshl_b32 s0, s20, 3
	s_add_u32 s0, s0, s14
	s_lshl_b32 s12, s0, 5
	s_mov_b32 s13, s12
	s_lshl_b32 s0, s20, 5
	s_add_u32 s1, s0, 0x1000
	s_cmp_eq_u32 s14, 8
	s_cselect_b32 s18, 1, 0
	s_cselect_b32 s12, s0, s12
	s_cselect_b32 s13, s1, s13
	s_nop 15
	s_nop 3
	s_cmp_lg_u32 s18, 0
	s_cbranch_scc1 .Lhp_ft_ctx1
	s_lshl_b32 s0, s17, 12
	s_add_u32 s0, s0, s12
	s_lshl_b32 s0, s0, 2
	s_add_u32 s10, s8, s0
	s_addc_u32 s11, s9, 0
	s_add_u32 s0, s10, 0x0
	s_addc_u32 s1, s11, 0
	global_store_dword v99, v64, s[0:1]
	s_add_u32 s0, s10, 0x4000
	s_addc_u32 s1, s11, 0
	global_store_dword v99, v65, s[0:1]
	s_add_u32 s0, s10, 0x8000
	s_addc_u32 s1, s11, 0
	global_store_dword v99, v66, s[0:1]
	s_add_u32 s0, s10, 0xc000
	s_addc_u32 s1, s11, 0
	global_store_dword v99, v67, s[0:1]
	s_add_u32 s0, s10, 0x20000
	s_addc_u32 s1, s11, 0
	global_store_dword v99, v68, s[0:1]
	s_add_u32 s0, s10, 0x24000
	s_addc_u32 s1, s11, 0
	global_store_dword v99, v69, s[0:1]
	s_add_u32 s0, s10, 0x28000
	s_addc_u32 s1, s11, 0
	global_store_dword v99, v70, s[0:1]
	s_add_u32 s0, s10, 0x2c000
	s_addc_u32 s1, s11, 0
	global_store_dword v99, v71, s[0:1]
	s_add_u32 s0, s10, 0x40000
	s_addc_u32 s1, s11, 0
	global_store_dword v99, v72, s[0:1]
	s_add_u32 s0, s10, 0x44000
	s_addc_u32 s1, s11, 0
	global_store_dword v99, v73, s[0:1]
	s_add_u32 s0, s10, 0x48000
	s_addc_u32 s1, s11, 0
	global_store_dword v99, v74, s[0:1]
	s_add_u32 s0, s10, 0x4c000
	s_addc_u32 s1, s11, 0
	global_store_dword v99, v75, s[0:1]
	s_add_u32 s0, s10, 0x60000
	s_addc_u32 s1, s11, 0
	global_store_dword v99, v76, s[0:1]
	s_add_u32 s0, s10, 0x64000
	s_addc_u32 s1, s11, 0
	global_store_dword v99, v77, s[0:1]
	s_add_u32 s0, s10, 0x68000
	s_addc_u32 s1, s11, 0
	global_store_dword v99, v78, s[0:1]
	s_add_u32 s0, s10, 0x6c000
	s_addc_u32 s1, s11, 0
	global_store_dword v99, v79, s[0:1]
	s_branch .Lhp_ft_next1

.Lhp_ft_next1:
	s_waitcnt vmcnt(16)
	s_add_u32 s14, s14, 1
	s_cmp_lt_u32 s14, s15
	s_cbranch_scc0 .Lhp_ft_done
	s_branch .Lhp_ft_tile
.Lhp_ft_done:
	s_mov_b32 s16, 0
